# guide 7.12: DSA score step order-key transform as shift/or/xor (no compare-select SGPR round trip)
# speedup vs baseline: 1.0070x; 1.0066x over previous
; DI f32x16 mfma32(bf16x8 a, bf16x8 b, f32x16 c) { return __builtin_amdgcn_mfma_f32_32x32x16_bf16(a, b, c, 0, 0, 0); }
; DI u32 mono_key(float f) { u32 u = __float_as_uint(f); return (u & 0x80000000u) ? ~u : (u | 0x80000000u); }
; DI void dsa_item(const Params& p, int l, int tile32, int b, char* smem) {
;     ...
;       for (int t = 0; t < 4; ++t) {
;         const int key = (g * 4 + t) * 32 + c31;
;         f32x16 acc;
; #pragma unroll
;         for (int j = 0; j < 16; ++j) acc[j] = 0.f;
; #pragma unroll
;         for (int s = 0; s < 4; ++s) acc = mfma32(qa[s], kc[t][s], acc);
;         f32x2 ss2 = f32x2{0.f, 0.f};
; #pragma unroll
;         for (int hq = 0; hq < 8; ++hq) {
;           const f32x2 rr = f32x2{__builtin_amdgcn_fmed3f(acc[2 * hq], 0.f, 3.0e38f), __builtin_amdgcn_fmed3f(acc[2 * hq + 1], 0.f, 3.0e38f)};
;           ss2 = __builtin_elementwise_fma(wq2[hq], rr, ss2);
;         }
;         const float s0 = ss2.x, s1 = ss2.y;
;         const u32 k0 = mono_key(s0), k1 = mono_key(s1);
;         const bool c0 = (key <= qpos0) && (k0 > tauA), c1 = (key <= qpos0 + 1) && (k1 > tauB);
;         const u64 m0 = __ballot(c0), m1 = __ballot(c1);
;         if (m0 | m1) {
;           const u32 h0 = hh ? (u32)(m0 >> 32) : (u32)m0, h1 = hh ? (u32)(m1 >> 32) : (u32)m1;
;           const int pA = (hh ? cnt2 : cnt0) + __popc(h0 & lmask), pB = (hh ? cnt3 : cnt1) + __popc(h1 & lmask);
;           if (c0) { ckey[(2 * hh) * DCAP + pA] = k0; cidx[(2 * hh) * DCAP + pA] = (u16)key; }
;           if (c1) { ckey[(2 * hh + 1) * DCAP + pB] = k1; cidx[(2 * hh + 1) * DCAP + pB] = (u16)key; }
;           cnt0 += __popc((u32)m0); cnt2 += __popc((u32)(m0 >> 32));
;           cnt1 += __popc((u32)m1); cnt3 += __popc((u32)(m1 >> 32));
;         }
.LBB0_499:
	s_or_b64 exec, exec, s[2:3]
	v_mfma_f32_32x32x16_bf16 v[2:17], v[18:21], v[2:5], 0
	v_cndmask_b32_e32 v0, v223, v224, vcc
	v_mfma_f32_32x32x16_bf16 v[2:17], v[22:25], v[98:101], v[2:17]
	v_mfma_f32_32x32x16_bf16 v[2:17], v[26:29], v[94:97], v[2:17]
	v_lshl_or_b32 v95, s54, 7, v192
	v_cndmask_b32_e32 v94, v221, v222, vcc
	v_cmp_le_i32_e64 s[0:1], v95, v217
	v_cmp_le_i32_e64 s[2:3], v95, v219
	v_mfma_f32_32x32x16_bf16 v[2:17], v[30:33], v[90:93], v[2:17]
	s_nop 11
	v_med3_f32 v2, v2, 0, v204
	v_med3_f32 v3, v3, 0, v204
	v_med3_f32 v4, v4, 0, v204
	v_med3_f32 v5, v5, 0, v204
	v_fma_f32 v2, v178, v2, 0
	v_fma_f32 v3, v179, v3, 0
	v_med3_f32 v6, v6, 0, v204
	v_med3_f32 v7, v7, 0, v204
	v_fmac_f32_e32 v2, v38, v4
	v_fmac_f32_e32 v3, v39, v5
	v_med3_f32 v8, v8, 0, v204
	v_med3_f32 v9, v9, 0, v204
	v_fmac_f32_e32 v2, v180, v6
	v_fmac_f32_e32 v3, v181, v7
	v_med3_f32 v10, v10, 0, v204
	v_med3_f32 v11, v11, 0, v204
	v_fmac_f32_e32 v2, v40, v8
	v_fmac_f32_e32 v3, v41, v9
	v_med3_f32 v12, v12, 0, v204
	v_med3_f32 v13, v13, 0, v204
	v_fmac_f32_e32 v2, v182, v10
	v_fmac_f32_e32 v3, v183, v11
	v_med3_f32 v14, v14, 0, v204
	v_med3_f32 v15, v15, 0, v204
	v_fmac_f32_e32 v2, v34, v12
	v_fmac_f32_e32 v3, v35, v13
	v_med3_f32 v16, v16, 0, v204
	v_med3_f32 v17, v17, 0, v204
	v_fmac_f32_e32 v2, v184, v14
	v_fmac_f32_e32 v3, v185, v15
	s_nop 0
	v_fma_f32 v4, v36, v16, v2
	v_fma_f32 v5, v37, v17, v3
	s_nop 0
	v_ashrrev_i32_e32 v2, 31, v4
	v_ashrrev_i32_e32 v6, 31, v5
	v_or_b32_e32 v2, 0x80000000, v2
	v_or_b32_e32 v6, 0x80000000, v6
	v_xor_b32_e32 v3, v4, v2
	v_xor_b32_e32 v2, v5, v6
	v_cmp_gt_u32_e64 s[4:5], v3, v0
	v_cmp_gt_u32_e64 s[6:7], v2, v94
	s_and_b64 s[10:11], s[0:1], s[4:5]
	s_and_b64 s[4:5], s[2:3], s[6:7]
	s_and_b64 s[0:1], s[10:11], exec
	s_and_b64 s[2:3], s[4:5], exec
	s_or_b64 s[6:7], s[2:3], s[0:1]
	s_cmp_eq_u64 s[6:7], 0
	s_cbranch_scc1 .LBB0_505
	s_and_saveexec_b64 s[6:7], s[10:11]
	s_cbranch_execz .LBB0_502
	v_mov_b32_e32 v4, s1
	v_mov_b32_e32 v5, s0
	v_cndmask_b32_e32 v4, v4, v5, vcc
	v_and_b32_e32 v4, v4, v218
	v_bcnt_u32_b32 v4, v4, 0
	v_cndmask_b32_e32 v5, v187, v173, vcc
	v_add3_u32 v4, v5, v214, v4
	v_lshl_add_u32 v5, v4, 2, v190
	ds_write_b32 v5, v3
	v_lshlrev_b32_e32 v3, 1, v4
	v_sub_u32_e32 v3, v5, v3
	ds_write_b16 v3, v95 offset:10240

; DI f32x16 mfma32(bf16x8 a, bf16x8 b, f32x16 c) { return __builtin_amdgcn_mfma_f32_32x32x16_bf16(a, b, c, 0, 0, 0); }
; DI u32 mono_key(float f) { u32 u = __float_as_uint(f); return (u & 0x80000000u) ? ~u : (u | 0x80000000u); }
; DI void dsa_item(const Params& p, int l, int tile32, int b, char* smem) {
;     ...
;       for (int t = 0; t < 4; ++t) {
;         const int key = (g * 4 + t) * 32 + c31;
;         f32x16 acc;
; #pragma unroll
;         for (int j = 0; j < 16; ++j) acc[j] = 0.f;
; #pragma unroll
;         for (int s = 0; s < 4; ++s) acc = mfma32(qa[s], kc[t][s], acc);
;         f32x2 ss2 = f32x2{0.f, 0.f};
; #pragma unroll
;         for (int hq = 0; hq < 8; ++hq) {
;           const f32x2 rr = f32x2{__builtin_amdgcn_fmed3f(acc[2 * hq], 0.f, 3.0e38f), __builtin_amdgcn_fmed3f(acc[2 * hq + 1], 0.f, 3.0e38f)};
;           ss2 = __builtin_elementwise_fma(wq2[hq], rr, ss2);
;         }
;         const float s0 = ss2.x, s1 = ss2.y;
;         const u32 k0 = mono_key(s0), k1 = mono_key(s1);
;         const bool c0 = (key <= qpos0) && (k0 > tauA), c1 = (key <= qpos0 + 1) && (k1 > tauB);
;         const u64 m0 = __ballot(c0), m1 = __ballot(c1);
;         if (m0 | m1) {
;           const u32 h0 = hh ? (u32)(m0 >> 32) : (u32)m0, h1 = hh ? (u32)(m1 >> 32) : (u32)m1;
;           const int pA = (hh ? cnt2 : cnt0) + __popc(h0 & lmask), pB = (hh ? cnt3 : cnt1) + __popc(h1 & lmask);
;           if (c0) { ckey[(2 * hh) * DCAP + pA] = k0; cidx[(2 * hh) * DCAP + pA] = (u16)key; }
;           if (c1) { ckey[(2 * hh + 1) * DCAP + pB] = k1; cidx[(2 * hh + 1) * DCAP + pB] = (u16)key; }
;           cnt0 += __popc((u32)m0); cnt2 += __popc((u32)(m0 >> 32));
;           cnt1 += __popc((u32)m1); cnt3 += __popc((u32)(m1 >> 32));
;         }
.LBB0_505:
	v_mfma_f32_32x32x16_bf16 v[2:17], v[18:21], v[86:89], 0
	v_mfma_f32_32x32x16_bf16 v[2:17], v[22:25], v[82:85], v[2:17]
	v_mfma_f32_32x32x16_bf16 v[2:17], v[26:29], v[78:81], v[2:17]
	v_or_b32_e32 v78, 32, v95
	v_cmp_le_i32_e64 s[0:1], v78, v217
	v_cmp_le_i32_e64 s[2:3], v78, v219
	v_mfma_f32_32x32x16_bf16 v[2:17], v[30:33], v[74:77], v[2:17]
	s_nop 11
	v_med3_f32 v2, v2, 0, v204
	v_med3_f32 v3, v3, 0, v204
	v_med3_f32 v4, v4, 0, v204
	v_med3_f32 v5, v5, 0, v204
	v_fma_f32 v2, v178, v2, 0
	v_fma_f32 v3, v179, v3, 0
	v_med3_f32 v6, v6, 0, v204
	v_med3_f32 v7, v7, 0, v204
	v_fmac_f32_e32 v2, v38, v4
	v_fmac_f32_e32 v3, v39, v5
	v_med3_f32 v8, v8, 0, v204
	v_med3_f32 v9, v9, 0, v204
	v_fmac_f32_e32 v2, v180, v6
	v_fmac_f32_e32 v3, v181, v7
	v_med3_f32 v10, v10, 0, v204
	v_med3_f32 v11, v11, 0, v204
	v_fmac_f32_e32 v2, v40, v8
	v_fmac_f32_e32 v3, v41, v9
	v_med3_f32 v12, v12, 0, v204
	v_med3_f32 v13, v13, 0, v204
	v_fmac_f32_e32 v2, v182, v10
	v_fmac_f32_e32 v3, v183, v11
	v_med3_f32 v14, v14, 0, v204
	v_med3_f32 v15, v15, 0, v204
	v_fmac_f32_e32 v2, v34, v12
	v_fmac_f32_e32 v3, v35, v13
	v_med3_f32 v16, v16, 0, v204
	v_med3_f32 v17, v17, 0, v204
	v_fmac_f32_e32 v2, v184, v14
	v_fmac_f32_e32 v3, v185, v15
	s_nop 0
	v_fma_f32 v4, v36, v16, v2
	v_fma_f32 v5, v37, v17, v3
	s_nop 0
	v_ashrrev_i32_e32 v2, 31, v4
	v_ashrrev_i32_e32 v6, 31, v5
	v_or_b32_e32 v2, 0x80000000, v2
	v_or_b32_e32 v6, 0x80000000, v6
	v_xor_b32_e32 v3, v4, v2
	v_xor_b32_e32 v2, v5, v6
	v_cmp_gt_u32_e64 s[4:5], v3, v0
	v_cmp_gt_u32_e64 s[6:7], v2, v94
	s_and_b64 s[10:11], s[0:1], s[4:5]
	s_and_b64 s[4:5], s[2:3], s[6:7]
	s_and_b64 s[2:3], s[10:11], exec
	s_and_b64 s[0:1], s[4:5], exec
	s_or_b64 s[6:7], s[0:1], s[2:3]
	s_cmp_eq_u64 s[6:7], 0
	s_cbranch_scc1 .LBB0_511
	s_and_saveexec_b64 s[6:7], s[10:11]
	s_cbranch_execz .LBB0_508
	v_mov_b32_e32 v4, s3
	v_mov_b32_e32 v5, s2
	v_cndmask_b32_e32 v4, v4, v5, vcc
	v_and_b32_e32 v4, v4, v218
	v_bcnt_u32_b32 v4, v4, 0
	v_cndmask_b32_e32 v5, v187, v173, vcc
	v_add3_u32 v4, v5, v214, v4
	v_lshl_add_u32 v5, v4, 2, v190
	ds_write_b32 v5, v3
	v_lshlrev_b32_e32 v3, 1, v4
	v_sub_u32_e32 v3, v5, v3
	ds_write_b16 v3, v78 offset:10240

; DI f32x16 mfma32(bf16x8 a, bf16x8 b, f32x16 c) { return __builtin_amdgcn_mfma_f32_32x32x16_bf16(a, b, c, 0, 0, 0); }
; DI u32 mono_key(float f) { u32 u = __float_as_uint(f); return (u & 0x80000000u) ? ~u : (u | 0x80000000u); }
; DI void dsa_item(const Params& p, int l, int tile32, int b, char* smem) {
;     ...
;       for (int t = 0; t < 4; ++t) {
;         const int key = (g * 4 + t) * 32 + c31;
;         f32x16 acc;
; #pragma unroll
;         for (int j = 0; j < 16; ++j) acc[j] = 0.f;
; #pragma unroll
;         for (int s = 0; s < 4; ++s) acc = mfma32(qa[s], kc[t][s], acc);
;         f32x2 ss2 = f32x2{0.f, 0.f};
; #pragma unroll
;         for (int hq = 0; hq < 8; ++hq) {
;           const f32x2 rr = f32x2{__builtin_amdgcn_fmed3f(acc[2 * hq], 0.f, 3.0e38f), __builtin_amdgcn_fmed3f(acc[2 * hq + 1], 0.f, 3.0e38f)};
;           ss2 = __builtin_elementwise_fma(wq2[hq], rr, ss2);
;         }
;         const float s0 = ss2.x, s1 = ss2.y;
;         const u32 k0 = mono_key(s0), k1 = mono_key(s1);
;         const bool c0 = (key <= qpos0) && (k0 > tauA), c1 = (key <= qpos0 + 1) && (k1 > tauB);
;         const u64 m0 = __ballot(c0), m1 = __ballot(c1);
;         if (m0 | m1) {
;           const u32 h0 = hh ? (u32)(m0 >> 32) : (u32)m0, h1 = hh ? (u32)(m1 >> 32) : (u32)m1;
;           const int pA = (hh ? cnt2 : cnt0) + __popc(h0 & lmask), pB = (hh ? cnt3 : cnt1) + __popc(h1 & lmask);
;           if (c0) { ckey[(2 * hh) * DCAP + pA] = k0; cidx[(2 * hh) * DCAP + pA] = (u16)key; }
;           if (c1) { ckey[(2 * hh + 1) * DCAP + pB] = k1; cidx[(2 * hh + 1) * DCAP + pB] = (u16)key; }
;           cnt0 += __popc((u32)m0); cnt2 += __popc((u32)(m0 >> 32));
;           cnt1 += __popc((u32)m1); cnt3 += __popc((u32)(m1 >> 32));
;         }
.LBB0_511:
	v_mfma_f32_32x32x16_bf16 v[2:17], v[18:21], v[70:73], 0
	v_mfma_f32_32x32x16_bf16 v[2:17], v[22:25], v[66:69], v[2:17]
	v_mfma_f32_32x32x16_bf16 v[2:17], v[26:29], v[62:65], v[2:17]
	v_or_b32_e32 v62, 64, v95
	v_cmp_le_i32_e64 s[0:1], v62, v217
	v_cmp_le_i32_e64 s[2:3], v62, v219
	v_mfma_f32_32x32x16_bf16 v[2:17], v[30:33], v[58:61], v[2:17]
	s_nop 11
	v_med3_f32 v2, v2, 0, v204
	v_med3_f32 v3, v3, 0, v204
	v_med3_f32 v4, v4, 0, v204
	v_med3_f32 v5, v5, 0, v204
	v_fma_f32 v2, v178, v2, 0
	v_fma_f32 v3, v179, v3, 0
	v_med3_f32 v6, v6, 0, v204
	v_med3_f32 v7, v7, 0, v204
	v_fmac_f32_e32 v2, v38, v4
	v_fmac_f32_e32 v3, v39, v5
	v_med3_f32 v8, v8, 0, v204
	v_med3_f32 v9, v9, 0, v204
	v_fmac_f32_e32 v2, v180, v6
	v_fmac_f32_e32 v3, v181, v7
	v_med3_f32 v10, v10, 0, v204
	v_med3_f32 v11, v11, 0, v204
	v_fmac_f32_e32 v2, v40, v8
	v_fmac_f32_e32 v3, v41, v9
	v_med3_f32 v12, v12, 0, v204
	v_med3_f32 v13, v13, 0, v204
	v_fmac_f32_e32 v2, v182, v10
	v_fmac_f32_e32 v3, v183, v11
	v_med3_f32 v14, v14, 0, v204
	v_med3_f32 v15, v15, 0, v204
	v_fmac_f32_e32 v2, v34, v12
	v_fmac_f32_e32 v3, v35, v13
	v_med3_f32 v16, v16, 0, v204
	v_med3_f32 v17, v17, 0, v204
	v_fmac_f32_e32 v2, v184, v14
	v_fmac_f32_e32 v3, v185, v15
	s_nop 0
	v_fma_f32 v4, v36, v16, v2
	v_fma_f32 v5, v37, v17, v3
	s_nop 0
	v_ashrrev_i32_e32 v2, 31, v4
	v_ashrrev_i32_e32 v6, 31, v5
	v_or_b32_e32 v2, 0x80000000, v2
	v_or_b32_e32 v6, 0x80000000, v6
	v_xor_b32_e32 v3, v4, v2
	v_xor_b32_e32 v2, v5, v6
	v_cmp_gt_u32_e64 s[4:5], v3, v0
	v_cmp_gt_u32_e64 s[6:7], v2, v94
	s_and_b64 s[10:11], s[0:1], s[4:5]
	s_and_b64 s[4:5], s[2:3], s[6:7]
	s_and_b64 s[2:3], s[10:11], exec
	s_and_b64 s[0:1], s[4:5], exec
	s_or_b64 s[6:7], s[0:1], s[2:3]
	s_cmp_eq_u64 s[6:7], 0
	s_cbranch_scc1 .LBB0_517
	s_and_saveexec_b64 s[6:7], s[10:11]
	s_cbranch_execz .LBB0_514
	v_mov_b32_e32 v4, s3
	v_mov_b32_e32 v5, s2
	v_cndmask_b32_e32 v4, v4, v5, vcc
	v_and_b32_e32 v4, v4, v218
	v_bcnt_u32_b32 v4, v4, 0
	v_cndmask_b32_e32 v5, v187, v173, vcc
	v_add3_u32 v4, v5, v214, v4
	v_lshl_add_u32 v5, v4, 2, v190
	ds_write_b32 v5, v3
	v_lshlrev_b32_e32 v3, 1, v4
	v_sub_u32_e32 v3, v5, v3
	ds_write_b16 v3, v62 offset:10240

; DI f32x16 mfma32(bf16x8 a, bf16x8 b, f32x16 c) { return __builtin_amdgcn_mfma_f32_32x32x16_bf16(a, b, c, 0, 0, 0); }
; DI u32 mono_key(float f) { u32 u = __float_as_uint(f); return (u & 0x80000000u) ? ~u : (u | 0x80000000u); }
; DI void dsa_item(const Params& p, int l, int tile32, int b, char* smem) {
;     ...
;       for (int t = 0; t < 4; ++t) {
;         const int key = (g * 4 + t) * 32 + c31;
;         f32x16 acc;
; #pragma unroll
;         for (int j = 0; j < 16; ++j) acc[j] = 0.f;
; #pragma unroll
;         for (int s = 0; s < 4; ++s) acc = mfma32(qa[s], kc[t][s], acc);
;         f32x2 ss2 = f32x2{0.f, 0.f};
; #pragma unroll
;         for (int hq = 0; hq < 8; ++hq) {
;           const f32x2 rr = f32x2{__builtin_amdgcn_fmed3f(acc[2 * hq], 0.f, 3.0e38f), __builtin_amdgcn_fmed3f(acc[2 * hq + 1], 0.f, 3.0e38f)};
;           ss2 = __builtin_elementwise_fma(wq2[hq], rr, ss2);
;         }
;         const float s0 = ss2.x, s1 = ss2.y;
;         const u32 k0 = mono_key(s0), k1 = mono_key(s1);
;         const bool c0 = (key <= qpos0) && (k0 > tauA), c1 = (key <= qpos0 + 1) && (k1 > tauB);
;         const u64 m0 = __ballot(c0), m1 = __ballot(c1);
;         if (m0 | m1) {
;           const u32 h0 = hh ? (u32)(m0 >> 32) : (u32)m0, h1 = hh ? (u32)(m1 >> 32) : (u32)m1;
;           const int pA = (hh ? cnt2 : cnt0) + __popc(h0 & lmask), pB = (hh ? cnt3 : cnt1) + __popc(h1 & lmask);
;           if (c0) { ckey[(2 * hh) * DCAP + pA] = k0; cidx[(2 * hh) * DCAP + pA] = (u16)key; }
;           if (c1) { ckey[(2 * hh + 1) * DCAP + pB] = k1; cidx[(2 * hh + 1) * DCAP + pB] = (u16)key; }
;           cnt0 += __popc((u32)m0); cnt2 += __popc((u32)(m0 >> 32));
;           cnt1 += __popc((u32)m1); cnt3 += __popc((u32)(m1 >> 32));
;         }
.LBB0_517:
	v_mfma_f32_32x32x16_bf16 v[2:17], v[18:21], v[54:57], 0
	v_mfma_f32_32x32x16_bf16 v[2:17], v[22:25], v[50:53], v[2:17]
	v_mfma_f32_32x32x16_bf16 v[2:17], v[26:29], v[46:49], v[2:17]
	v_or_b32_e32 v46, 0x60, v95
	v_cmp_le_i32_e64 s[0:1], v46, v217
	v_cmp_le_i32_e64 s[2:3], v46, v219
	v_mfma_f32_32x32x16_bf16 v[2:17], v[30:33], v[42:45], v[2:17]
	s_nop 11
	v_med3_f32 v2, v2, 0, v204
	v_med3_f32 v3, v3, 0, v204
	v_med3_f32 v4, v4, 0, v204
	v_med3_f32 v5, v5, 0, v204
	v_fma_f32 v2, v178, v2, 0
	v_fma_f32 v3, v179, v3, 0
	v_med3_f32 v6, v6, 0, v204
	v_med3_f32 v7, v7, 0, v204
	v_fmac_f32_e32 v2, v38, v4
	v_fmac_f32_e32 v3, v39, v5
	v_med3_f32 v8, v8, 0, v204
	v_med3_f32 v9, v9, 0, v204
	v_fmac_f32_e32 v2, v180, v6
	v_fmac_f32_e32 v3, v181, v7
	v_med3_f32 v10, v10, 0, v204
	v_med3_f32 v11, v11, 0, v204
	v_fmac_f32_e32 v2, v40, v8
	v_fmac_f32_e32 v3, v41, v9
	v_med3_f32 v12, v12, 0, v204
	v_med3_f32 v13, v13, 0, v204
	v_fmac_f32_e32 v2, v182, v10
	v_fmac_f32_e32 v3, v183, v11
	v_med3_f32 v14, v14, 0, v204
	v_med3_f32 v15, v15, 0, v204
	v_fmac_f32_e32 v2, v34, v12
	v_fmac_f32_e32 v3, v35, v13
	v_med3_f32 v16, v16, 0, v204
	v_med3_f32 v17, v17, 0, v204
	v_fmac_f32_e32 v2, v184, v14
	v_fmac_f32_e32 v3, v185, v15
	s_nop 0
	v_fma_f32 v4, v36, v16, v2
	v_fma_f32 v5, v37, v17, v3
	s_nop 0
	v_ashrrev_i32_e32 v2, 31, v4
	v_ashrrev_i32_e32 v6, 31, v5
	v_or_b32_e32 v2, 0x80000000, v2
	v_or_b32_e32 v6, 0x80000000, v6
	v_xor_b32_e32 v3, v4, v2
	v_xor_b32_e32 v2, v5, v6
	v_cmp_gt_u32_e64 s[4:5], v3, v0
	v_cmp_gt_u32_e64 s[6:7], v2, v94
	s_and_b64 s[10:11], s[0:1], s[4:5]
	s_and_b64 s[4:5], s[2:3], s[6:7]
	s_and_b64 s[2:3], s[10:11], exec
	s_and_b64 s[0:1], s[4:5], exec
	s_or_b64 s[6:7], s[0:1], s[2:3]
	s_cmp_eq_u64 s[6:7], 0
	s_cbranch_scc1 .LBB0_374
	s_and_saveexec_b64 s[6:7], s[10:11]
	s_cbranch_execz .LBB0_520
	v_mov_b32_e32 v0, s3
	v_mov_b32_e32 v4, s2
	v_cndmask_b32_e32 v0, v0, v4, vcc
	v_and_b32_e32 v0, v0, v218
	v_bcnt_u32_b32 v0, v0, 0
	v_cndmask_b32_e32 v4, v187, v173, vcc
	v_add3_u32 v0, v4, v214, v0
	v_lshl_add_u32 v4, v0, 2, v190
	v_lshlrev_b32_e32 v0, 1, v0
	v_sub_u32_e32 v0, v4, v0
	ds_write_b32 v4, v3
	ds_write_b16 v0, v46 offset:10240
